# dsa_attn epilogue: 32 two-byte stores per item replaced by LDS staging + one 16-byte-per-lane store; plus f32-MFMA xa_pass and dsa_topk changes
# speedup vs baseline: 1.0167x; 1.0046x over previous
; #define LAS __attribute__((address_space(3)))
; #define ATTN_VLOAD(dst, ks) do { const int sreg_ = ((ks) < 2) ? s0 : ((ks) < 4) ? s1 : ((ks) < 6) ? s2 : s3; _Pragma("unroll") for (int i = 0; i < 8; ++i) { \
;             const int idx_ = shi(sreg_, 32 * ((ks) & 1) + fq + 4 * i); dst[i] = *(const u32x4*)(vbase + (size_t)idx_ * DSA_NP); } } while (0)
; __device__ __forceinline__ void dsa_attn(const bf16_t* DP, const int* SEL, bf16_t* O, LAS unsigned char* lds, int widk) {
;     ...
; #pragma unroll
;         for (int ks = 0; ks < 8; ++ks) {
;             if (ks < 6) ATTN_VLOAD(vnn, ks + 2);
; #pragma unroll
;             for (int i = 0; i < 8; ++i) { const unsigned row = (unsigned)(fq + 4 * i), ch = (unsigned)fr;
;                 *(LAS u32x4*)(vt + 256u * row + 16u * (ch ^ (((row & 3u) << 2) | ((row >> 2) & 3u)))) = vcur[i]; }
;             bf16x8 pa = (bf16x8){0, 0, 0, 0, 0, 0, 0, 0};
;             asm volatile("s_waitcnt lgkmcnt(0)" ::: "memory");
;             if (fr < 4) pa = *(const LAS bf16x8*)(pl + (fr * 256 + 32 * ks + 8 * fq) * 2);
;             u32x2 t0[8], t1[8];
; #pragma unroll
;             for (int cb = 0; cb < 8; ++cb) {
;                 asm volatile("ds_read_b64_tr_b16 %0, %1" : "=v"(t0[cb]) : "v"(tra[cb][0]) : "memory");
;                 asm volatile("ds_read_b64_tr_b16 %0, %1" : "=v"(t1[cb]) : "v"(tra[cb][1]) : "memory");
;             }
;             asm volatile("s_waitcnt lgkmcnt(0)" : "+v"(t0[0]), "+v"(t0[1]), "+v"(t0[2]), "+v"(t0[3]), "+v"(t0[4]), "+v"(t0[5]), "+v"(t0[6]), "+v"(t0[7]),
;                                                   "+v"(t1[0]), "+v"(t1[1]), "+v"(t1[2]), "+v"(t1[3]), "+v"(t1[4]), "+v"(t1[5]), "+v"(t1[6]), "+v"(t1[7]), "+v"(pa) :: "memory");
; #pragma unroll
;             for (int cb = 0; cb < 8; ++cb) { const u32x4 bw = {t0[cb].x, t0[cb].y, t1[cb].x, t1[cb].y};
;                 oc[cb] = __builtin_amdgcn_mfma_f32_16x16x32_bf16(pa, __builtin_bit_cast(bf16x8, bw), oc[cb], 0, 0, 0); }
; #pragma unroll
;             for (int i = 0; i < 8; ++i) { vcur[i] = vnxt[i]; vnxt[i] = vnn[i]; }
;         }
.LBB0_673:
	s_or_b64 exec, exec, s[6:7]
	ds_bpermute_b32 v66, v167, v135
	ds_bpermute_b32 v68, v175, v135
	ds_bpermute_b32 v74, v176, v135
	ds_bpermute_b32 v75, v177, v135
	v_add_u32_e32 v149, v171, v142
	s_waitcnt lgkmcnt(3)
	v_mad_i64_i32 v[66:67], s[6:7], v66, s62, v[150:151]
	s_waitcnt lgkmcnt(2)
	v_mad_i64_i32 v[68:69], s[6:7], v68, s62, v[150:151]
	global_load_dwordx4 v[70:73], v[66:67], off
	global_load_dwordx4 v[82:85], v[68:69], off
	s_waitcnt lgkmcnt(1)
	v_mad_i64_i32 v[66:67], s[6:7], v74, s62, v[150:151]
	ds_bpermute_b32 v74, v178, v135
	s_waitcnt lgkmcnt(1)
	v_mad_i64_i32 v[68:69], s[6:7], v75, s62, v[150:151]
	ds_bpermute_b32 v75, v179, v135
	global_load_dwordx4 v[86:89], v[66:67], off
	global_load_dwordx4 v[90:93], v[68:69], off
	s_waitcnt lgkmcnt(1)
	v_mad_i64_i32 v[66:67], s[6:7], v74, s62, v[150:151]
	ds_bpermute_b32 v74, v180, v135
	s_waitcnt lgkmcnt(1)
	v_mad_i64_i32 v[68:69], s[6:7], v75, s62, v[150:151]
	ds_bpermute_b32 v75, v181, v135
	global_load_dwordx4 v[102:105], v[66:67], off
	global_load_dwordx4 v[106:109], v[68:69], off
	s_waitcnt lgkmcnt(1)
	v_mad_i64_i32 v[66:67], s[6:7], v74, s62, v[150:151]
	s_waitcnt lgkmcnt(0)
	v_mad_i64_i32 v[68:69], s[6:7], v75, s62, v[150:151]
	global_load_dwordx4 v[110:113], v[66:67], off
	global_load_dwordx4 v[114:117], v[68:69], off
	s_waitcnt vmcnt(22)
	ds_write_b128 v249, v[22:25] offset:2048
	s_waitcnt vmcnt(19)
	ds_write_b128 v250, v[38:41] offset:3072
	s_waitcnt vmcnt(17)
	ds_write_b128 v251, v[42:45] offset:4096
	s_waitcnt vmcnt(14)
	ds_write_b128 v240, v[46:49] offset:5120
	s_waitcnt vmcnt(13)
	ds_write_b128 v249, v[50:53] offset:6144
	s_waitcnt vmcnt(12)
	ds_write_b128 v250, v[54:57] offset:7168
	s_waitcnt vmcnt(11)
	ds_write_b128 v251, v[58:61] offset:8192
	s_waitcnt vmcnt(10)
	ds_write_b128 v240, v[62:65] offset:9216
	s_waitcnt lgkmcnt(0)
	v_mov_b32_e32 v54, 0
	v_mov_b32_e32 v22, 0
	v_mov_b32_e32 v23, 0
	v_mov_b32_e32 v24, 0
	v_mov_b32_e32 v25, 0
	s_and_saveexec_b64 s[6:7], s[0:1]
	ds_read_b128 v[22:25], v149
	s_or_b64 exec, exec, s[6:7]
	ds_read_b64_tr_b16 v[38:39], v139
	ds_read_b64_tr_b16 v[40:41], v152
	ds_read_b64_tr_b16 v[42:43], v153
	ds_read_b64_tr_b16 v[44:45], v154
	ds_read_b64_tr_b16 v[46:47], v155
	ds_read_b64_tr_b16 v[48:49], v156
	ds_read_b64_tr_b16 v[50:51], v157
	ds_read_b64_tr_b16 v[52:53], v158
	ds_read_b64_tr_b16 v[62:63], v159
	ds_read_b64_tr_b16 v[64:65], v160
	ds_read_b64_tr_b16 v[74:75], v161
	ds_read_b64_tr_b16 v[76:77], v162
	ds_read_b64_tr_b16 v[94:95], v163
	ds_read_b64_tr_b16 v[96:97], v164
	ds_bpermute_b32 v55, v186, v135
	ds_read_b64_tr_b16 v[130:131], v165
	ds_read_b64_tr_b16 v[132:133], v166
	s_waitcnt lgkmcnt(0)
	v_mad_i64_i32 v[56:57], s[6:7], v55, s62, v[150:151]
	s_waitcnt lgkmcnt(0)
	ds_bpermute_b32 v55, v187, v135
	v_mfma_f32_16x16x32_bf16 v[98:101], v[22:25], v[50:53], 0
	ds_bpermute_b32 v50, v185, v135
	s_waitcnt lgkmcnt(0)
	v_mad_i64_i32 v[50:51], s[6:7], v50, s62, v[150:151]
	v_mfma_f32_16x16x32_bf16 v[58:61], v[22:25], v[38:41], 0
	ds_bpermute_b32 v38, v182, v135
	global_load_dwordx4 v[50:53], v[50:51], off
	s_waitcnt lgkmcnt(0)
	v_mad_i64_i32 v[38:39], s[6:7], v38, s62, v[150:151]
	v_mfma_f32_16x16x32_bf16 v[66:69], v[22:25], v[42:45], 0
	ds_bpermute_b32 v42, v183, v135
	global_load_dwordx4 v[38:41], v[38:39], off
	s_waitcnt lgkmcnt(0)
	v_mad_i64_i32 v[42:43], s[6:7], v42, s62, v[150:151]
	v_mfma_f32_16x16x32_bf16 v[78:81], v[22:25], v[46:49], 0
	ds_bpermute_b32 v46, v184, v135
	global_load_dwordx4 v[42:45], v[42:43], off
	s_waitcnt lgkmcnt(0)
	v_mad_i64_i32 v[46:47], s[6:7], v46, s62, v[150:151]
	v_mfma_f32_16x16x32_bf16 v[118:121], v[22:25], v[62:65], 0
	global_load_dwordx4 v[62:65], v[56:57], off
	v_mad_i64_i32 v[56:57], s[6:7], v55, s62, v[150:151]
	v_mfma_f32_16x16x32_bf16 v[122:125], v[22:25], v[74:77], 0
	ds_bpermute_b32 v55, v188, v135
	global_load_dwordx4 v[74:77], v[56:57], off
	s_waitcnt lgkmcnt(0)
	v_mad_i64_i32 v[56:57], s[6:7], v55, s62, v[150:151]
	v_mfma_f32_16x16x32_bf16 v[126:129], v[22:25], v[94:97], 0
	global_load_dwordx4 v[46:49], v[46:47], off
	v_mov_b32_e32 v55, 0
	global_load_dwordx4 v[94:97], v[56:57], off
	v_mfma_f32_16x16x32_bf16 v[130:133], v[22:25], v[130:133], 0
	ds_bpermute_b32 v22, v168, v135
	v_mov_b32_e32 v56, 0
	v_mov_b32_e32 v57, 0
	s_waitcnt lgkmcnt(0)
	v_mad_i64_i32 v[22:23], s[6:7], v22, s62, v[150:151]
	global_load_dwordx4 v[22:25], v[22:23], off
	s_waitcnt vmcnt(17)
	ds_write_b128 v249, v[2:5] offset:2048
	ds_write_b128 v250, v[6:9] offset:3072
	ds_write_b128 v251, v[10:13] offset:4096
	ds_write_b128 v240, v[14:17] offset:5120
	ds_write_b128 v249, v[18:21] offset:6144
	ds_write_b128 v250, v[26:29] offset:7168
	ds_write_b128 v251, v[30:33] offset:8192
	s_waitcnt vmcnt(16)
	ds_write_b128 v240, v[34:37] offset:9216
	s_waitcnt lgkmcnt(0)
	s_and_saveexec_b64 s[6:7], s[0:1]
	ds_read_b128 v[54:57], v149 offset:64
	s_or_b64 exec, exec, s[6:7]
	ds_read_b64_tr_b16 v[2:3], v139
	ds_read_b64_tr_b16 v[4:5], v152
	ds_read_b64_tr_b16 v[10:11], v153
	ds_read_b64_tr_b16 v[12:13], v154
	ds_read_b64_tr_b16 v[18:19], v155
	ds_read_b64_tr_b16 v[20:21], v156
	ds_read_b64_tr_b16 v[30:31], v157
	ds_read_b64_tr_b16 v[32:33], v158
	ds_read_b64_tr_b16 v[202:203], v159
	ds_read_b64_tr_b16 v[204:205], v160
	ds_read_b64_tr_b16 v[190:191], v161
	ds_read_b64_tr_b16 v[192:193], v162
	ds_read_b64_tr_b16 v[194:195], v163
	ds_read_b64_tr_b16 v[196:197], v164
	ds_read_b64_tr_b16 v[198:199], v165
	ds_read_b64_tr_b16 v[200:201], v166
	s_waitcnt lgkmcnt(0)
	s_waitcnt lgkmcnt(0)
	s_nop 0
	v_mfma_f32_16x16x32_bf16 v[6:9], v[54:57], v[2:5], v[58:61]
	ds_bpermute_b32 v2, v167, v134
	s_waitcnt lgkmcnt(0)
; #define LAS __attribute__((address_space(3)))
; #define ATTN_VLOAD(dst, ks) do { const int sreg_ = ((ks) < 2) ? s0 : ((ks) < 4) ? s1 : ((ks) < 6) ? s2 : s3; _Pragma("unroll") for (int i = 0; i < 8; ++i) { \
;             const int idx_ = shi(sreg_, 32 * ((ks) & 1) + fq + 4 * i); dst[i] = *(const u32x4*)(vbase + (size_t)idx_ * DSA_NP); } } while (0)
; __device__ __forceinline__ void dsa_attn(const bf16_t* DP, const int* SEL, bf16_t* O, LAS unsigned char* lds, int widk) {
;     ...
; #pragma unroll
;         for (int ks = 0; ks < 8; ++ks) {
;             if (ks < 6) ATTN_VLOAD(vnn, ks + 2);
; #pragma unroll
;             for (int i = 0; i < 8; ++i) { const unsigned row = (unsigned)(fq + 4 * i), ch = (unsigned)fr;
;                 *(LAS u32x4*)(vt + 256u * row + 16u * (ch ^ (((row & 3u) << 2) | ((row >> 2) & 3u)))) = vcur[i]; }
;             bf16x8 pa = (bf16x8){0, 0, 0, 0, 0, 0, 0, 0};
;             asm volatile("s_waitcnt lgkmcnt(0)" ::: "memory");
;             if (fr < 4) pa = *(const LAS bf16x8*)(pl + (fr * 256 + 32 * ks + 8 * fq) * 2);
;             u32x2 t0[8], t1[8];
; #pragma unroll
;             for (int cb = 0; cb < 8; ++cb) {
;                 asm volatile("ds_read_b64_tr_b16 %0, %1" : "=v"(t0[cb]) : "v"(tra[cb][0]) : "memory");
;                 asm volatile("ds_read_b64_tr_b16 %0, %1" : "=v"(t1[cb]) : "v"(tra[cb][1]) : "memory");
;             }
;             asm volatile("s_waitcnt lgkmcnt(0)" : "+v"(t0[0]), "+v"(t0[1]), "+v"(t0[2]), "+v"(t0[3]), "+v"(t0[4]), "+v"(t0[5]), "+v"(t0[6]), "+v"(t0[7]),
;                                                   "+v"(t1[0]), "+v"(t1[1]), "+v"(t1[2]), "+v"(t1[3]), "+v"(t1[4]), "+v"(t1[5]), "+v"(t1[6]), "+v"(t1[7]), "+v"(pa) :: "memory");
; #pragma unroll
;             for (int cb = 0; cb < 8; ++cb) { const u32x4 bw = {t0[cb].x, t0[cb].y, t1[cb].x, t1[cb].y};
;                 oc[cb] = __builtin_amdgcn_mfma_f32_16x16x32_bf16(pa, __builtin_bit_cast(bf16x8, bw), oc[cb], 0, 0, 0); }
; #pragma unroll
;             for (int i = 0; i < 8; ++i) { vcur[i] = vnxt[i]; vnxt[i] = vnn[i]; }
;         }
	v_mad_i64_i32 v[2:3], s[6:7], v2, s62, v[150:151]
	v_mfma_f32_16x16x32_bf16 v[14:17], v[54:57], v[10:13], v[66:69]
	ds_bpermute_b32 v10, v175, v134
	global_load_dwordx4 v[2:5], v[2:3], off
	s_waitcnt lgkmcnt(0)
	v_mad_i64_i32 v[10:11], s[6:7], v10, s62, v[150:151]
	v_mfma_f32_16x16x32_bf16 v[26:29], v[54:57], v[18:21], v[78:81]
	ds_bpermute_b32 v18, v176, v134
	ds_bpermute_b32 v66, v179, v134
	global_load_dwordx4 v[10:13], v[10:11], off
	v_mfma_f32_16x16x32_bf16 v[34:37], v[54:57], v[30:33], v[98:101]
	ds_bpermute_b32 v30, v177, v134
	ds_bpermute_b32 v78, v180, v134
	s_waitcnt lgkmcnt(3)
	v_mad_i64_i32 v[18:19], s[6:7], v18, s62, v[150:151]
	v_mfma_f32_16x16x32_bf16 v[58:61], v[54:57], v[202:205], v[118:121]
	ds_bpermute_b32 v98, v181, v134
	s_waitcnt lgkmcnt(2)
	v_mad_i64_i32 v[30:31], s[6:7], v30, s62, v[150:151]
	v_mfma_f32_16x16x32_bf16 v[118:121], v[54:57], v[190:193], v[122:125]
	v_mad_i64_i32 v[66:67], s[6:7], v66, s62, v[150:151]
	s_waitcnt lgkmcnt(1)
	v_mad_i64_i32 v[78:79], s[6:7], v78, s62, v[150:151]
	v_mfma_f32_16x16x32_bf16 v[122:125], v[54:57], v[194:197], v[126:129]
	s_waitcnt lgkmcnt(0)
	v_mad_i64_i32 v[98:99], s[6:7], v98, s62, v[150:151]
	global_load_dwordx4 v[18:21], v[18:19], off
	v_mfma_f32_16x16x32_bf16 v[126:129], v[54:57], v[198:201], v[130:133]
	ds_bpermute_b32 v54, v178, v134
	global_load_dwordx4 v[30:33], v[30:31], off
	s_waitcnt lgkmcnt(0)
	v_mad_i64_i32 v[54:55], s[6:7], v54, s62, v[150:151]
	global_load_dwordx4 v[54:57], v[54:55], off
	s_nop 0
	global_load_dwordx4 v[66:69], v[66:67], off
	s_nop 0
	global_load_dwordx4 v[78:81], v[78:79], off
	s_nop 0
	global_load_dwordx4 v[98:101], v[98:99], off
	s_waitcnt vmcnt(23)
	ds_write_b128 v249, v[70:73] offset:2048
	s_waitcnt vmcnt(22)
	ds_write_b128 v250, v[82:85] offset:3072
	s_waitcnt vmcnt(21)
	ds_write_b128 v251, v[86:89] offset:4096
	s_waitcnt vmcnt(20)
	ds_write_b128 v240, v[90:93] offset:5120
	s_waitcnt vmcnt(19)
	ds_write_b128 v249, v[102:105] offset:6144
	s_waitcnt vmcnt(18)
	ds_write_b128 v250, v[106:109] offset:7168
	s_waitcnt vmcnt(17)
	ds_write_b128 v251, v[110:113] offset:8192
	s_waitcnt vmcnt(16)
	ds_write_b128 v240, v[114:117] offset:9216
	s_waitcnt lgkmcnt(0)
	v_mov_b32_e32 v90, 0
	v_mov_b32_e32 v70, 0
	v_mov_b32_e32 v71, 0
	v_mov_b32_e32 v72, 0
	v_mov_b32_e32 v73, 0
	s_and_saveexec_b64 s[6:7], s[0:1]
	ds_read_b128 v[70:73], v149 offset:128
	s_or_b64 exec, exec, s[6:7]
	ds_read_b64_tr_b16 v[82:83], v139
	ds_read_b64_tr_b16 v[84:85], v152
	ds_read_b64_tr_b16 v[86:87], v153
	ds_read_b64_tr_b16 v[88:89], v154
	ds_read_b64_tr_b16 v[110:111], v155
	ds_read_b64_tr_b16 v[112:113], v156
	ds_read_b64_tr_b16 v[114:115], v157
	ds_read_b64_tr_b16 v[116:117], v158
	ds_read_b64_tr_b16 v[130:131], v159
	ds_read_b64_tr_b16 v[132:133], v160
	ds_read_b64_tr_b16 v[190:191], v161
	ds_read_b64_tr_b16 v[192:193], v162
	ds_read_b64_tr_b16 v[194:195], v163
	ds_read_b64_tr_b16 v[196:197], v164
	ds_read_b64_tr_b16 v[198:199], v165
	ds_read_b64_tr_b16 v[200:201], v166
	v_mov_b32_e32 v91, 0
	s_waitcnt lgkmcnt(0)
	s_waitcnt lgkmcnt(0)
	v_mov_b32_e32 v92, 0
	v_mfma_f32_16x16x32_bf16 v[102:105], v[70:73], v[82:85], v[6:9]
	ds_bpermute_b32 v82, v187, v134
	v_mov_b32_e32 v93, 0
	s_waitcnt lgkmcnt(0)
	v_mad_i64_i32 v[82:83], s[6:7], v82, s62, v[150:151]
	v_mfma_f32_16x16x32_bf16 v[106:109], v[70:73], v[86:89], v[14:17]
	ds_bpermute_b32 v6, v168, v134
	ds_bpermute_b32 v86, v188, v134
	global_load_dwordx4 v[82:85], v[82:83], off
	v_mfma_f32_16x16x32_bf16 v[110:113], v[70:73], v[110:113], v[26:29]
	ds_bpermute_b32 v14, v182, v134
	s_waitcnt lgkmcnt(2)
	v_mad_i64_i32 v[6:7], s[6:7], v6, s62, v[150:151]
	v_mfma_f32_16x16x32_bf16 v[114:117], v[70:73], v[114:117], v[34:37]
	ds_bpermute_b32 v26, v183, v134
	s_waitcnt lgkmcnt(1)
	v_mad_i64_i32 v[14:15], s[6:7], v14, s62, v[150:151]
	v_mfma_f32_16x16x32_bf16 v[130:133], v[70:73], v[130:133], v[58:61]
	ds_bpermute_b32 v34, v184, v134
	s_waitcnt lgkmcnt(1)
	v_mad_i64_i32 v[26:27], s[6:7], v26, s62, v[150:151]
	v_mfma_f32_16x16x32_bf16 v[118:121], v[70:73], v[190:193], v[118:121]
	ds_bpermute_b32 v58, v185, v134
	s_waitcnt lgkmcnt(1)
	v_mad_i64_i32 v[34:35], s[6:7], v34, s62, v[150:151]
	v_mfma_f32_16x16x32_bf16 v[122:125], v[70:73], v[194:197], v[122:125]
	v_mad_i64_i32 v[86:87], s[6:7], v86, s62, v[150:151]
	s_waitcnt lgkmcnt(0)
	v_mad_i64_i32 v[58:59], s[6:7], v58, s62, v[150:151]
	v_mfma_f32_16x16x32_bf16 v[126:129], v[70:73], v[198:201], v[126:129]
	ds_bpermute_b32 v70, v186, v134
	global_load_dwordx4 v[6:9], v[6:7], off
	s_waitcnt lgkmcnt(0)
	v_mad_i64_i32 v[70:71], s[6:7], v70, s62, v[150:151]
	global_load_dwordx4 v[14:17], v[14:15], off
	s_nop 0
	global_load_dwordx4 v[26:29], v[26:27], off
	s_nop 0
	global_load_dwordx4 v[34:37], v[34:35], off
	s_nop 0
	global_load_dwordx4 v[58:61], v[58:59], off
	s_nop 0
	global_load_dwordx4 v[70:73], v[70:71], off
	s_nop 0
	global_load_dwordx4 v[86:89], v[86:87], off
	s_waitcnt vmcnt(16)
	ds_write_b128 v249, v[22:25] offset:2048
	ds_write_b128 v250, v[38:41] offset:3072
	ds_write_b128 v251, v[42:45] offset:4096
	ds_write_b128 v240, v[46:49] offset:5120
	ds_write_b128 v249, v[50:53] offset:6144
	ds_write_b128 v250, v[62:65] offset:7168
	ds_write_b128 v251, v[74:77] offset:8192
	ds_write_b128 v240, v[94:97] offset:9216
	s_waitcnt lgkmcnt(0)
	s_and_saveexec_b64 s[6:7], s[0:1]
	ds_read_b128 v[90:93], v149 offset:192
	s_or_b64 exec, exec, s[6:7]
	ds_read_b64_tr_b16 v[22:23], v139
	ds_read_b64_tr_b16 v[24:25], v152
	ds_read_b64_tr_b16 v[38:39], v153
	ds_read_b64_tr_b16 v[40:41], v154
	ds_read_b64_tr_b16 v[42:43], v155
	ds_read_b64_tr_b16 v[44:45], v156
	ds_read_b64_tr_b16 v[46:47], v157
	ds_read_b64_tr_b16 v[48:49], v158
	ds_read_b64_tr_b16 v[50:51], v159
	ds_read_b64_tr_b16 v[52:53], v160
	ds_read_b64_tr_b16 v[62:63], v161
	ds_read_b64_tr_b16 v[64:65], v162
	ds_read_b64_tr_b16 v[74:75], v163
	ds_read_b64_tr_b16 v[76:77], v164
	ds_read_b64_tr_b16 v[134:135], v165
	ds_read_b64_tr_b16 v[136:137], v166
	s_waitcnt lgkmcnt(0)
; #define LAS __attribute__((address_space(3)))
; #define ATTN_VLOAD(dst, ks) do { const int sreg_ = ((ks) < 2) ? s0 : ((ks) < 4) ? s1 : ((ks) < 6) ? s2 : s3; _Pragma("unroll") for (int i = 0; i < 8; ++i) { \
;             const int idx_ = shi(sreg_, 32 * ((ks) & 1) + fq + 4 * i); dst[i] = *(const u32x4*)(vbase + (size_t)idx_ * DSA_NP); } } while (0)
; __device__ __forceinline__ void dsa_attn(const bf16_t* DP, const int* SEL, bf16_t* O, LAS unsigned char* lds, int widk) {
;     ...
; #pragma unroll
;         for (int ks = 0; ks < 8; ++ks) {
;             if (ks < 6) ATTN_VLOAD(vnn, ks + 2);
; #pragma unroll
;             for (int i = 0; i < 8; ++i) { const unsigned row = (unsigned)(fq + 4 * i), ch = (unsigned)fr;
;                 *(LAS u32x4*)(vt + 256u * row + 16u * (ch ^ (((row & 3u) << 2) | ((row >> 2) & 3u)))) = vcur[i]; }
;             bf16x8 pa = (bf16x8){0, 0, 0, 0, 0, 0, 0, 0};
;             asm volatile("s_waitcnt lgkmcnt(0)" ::: "memory");
;             if (fr < 4) pa = *(const LAS bf16x8*)(pl + (fr * 256 + 32 * ks + 8 * fq) * 2);
;             u32x2 t0[8], t1[8];
; #pragma unroll
;             for (int cb = 0; cb < 8; ++cb) {
;                 asm volatile("ds_read_b64_tr_b16 %0, %1" : "=v"(t0[cb]) : "v"(tra[cb][0]) : "memory");
;                 asm volatile("ds_read_b64_tr_b16 %0, %1" : "=v"(t1[cb]) : "v"(tra[cb][1]) : "memory");
;             }
;             asm volatile("s_waitcnt lgkmcnt(0)" : "+v"(t0[0]), "+v"(t0[1]), "+v"(t0[2]), "+v"(t0[3]), "+v"(t0[4]), "+v"(t0[5]), "+v"(t0[6]), "+v"(t0[7]),
;                                                   "+v"(t1[0]), "+v"(t1[1]), "+v"(t1[2]), "+v"(t1[3]), "+v"(t1[4]), "+v"(t1[5]), "+v"(t1[6]), "+v"(t1[7]), "+v"(pa) :: "memory");
; #pragma unroll
;             for (int cb = 0; cb < 8; ++cb) { const u32x4 bw = {t0[cb].x, t0[cb].y, t1[cb].x, t1[cb].y};
;                 oc[cb] = __builtin_amdgcn_mfma_f32_16x16x32_bf16(pa, __builtin_bit_cast(bf16x8, bw), oc[cb], 0, 0, 0); }
; #pragma unroll
;             for (int i = 0; i < 8; ++i) { vcur[i] = vnxt[i]; vnxt[i] = vnn[i]; }
;         }
	s_waitcnt lgkmcnt(0)
	s_nop 0
	v_mfma_f32_16x16x32_bf16 v[94:97], v[90:93], v[22:25], v[102:105]
	ds_bpermute_b32 v22, v167, v241
	s_waitcnt lgkmcnt(0)
	v_mad_i64_i32 v[22:23], s[6:7], v22, s62, v[150:151]
	v_mfma_f32_16x16x32_bf16 v[102:105], v[90:93], v[38:41], v[106:109]
	ds_bpermute_b32 v38, v175, v241
	global_load_dwordx4 v[22:25], v[22:23], off
	s_waitcnt lgkmcnt(0)
	v_mad_i64_i32 v[38:39], s[6:7], v38, s62, v[150:151]
	v_mfma_f32_16x16x32_bf16 v[106:109], v[90:93], v[42:45], v[110:113]
	ds_bpermute_b32 v42, v176, v241
	global_load_dwordx4 v[38:41], v[38:39], off
	s_waitcnt lgkmcnt(0)
	v_mad_i64_i32 v[42:43], s[6:7], v42, s62, v[150:151]
	v_mfma_f32_16x16x32_bf16 v[110:113], v[90:93], v[46:49], v[114:117]
	ds_bpermute_b32 v46, v177, v241
	global_load_dwordx4 v[42:45], v[42:43], off
	s_waitcnt lgkmcnt(0)
	v_mad_i64_i32 v[46:47], s[6:7], v46, s62, v[150:151]
	v_mfma_f32_16x16x32_bf16 v[114:117], v[90:93], v[50:53], v[130:133]
	ds_bpermute_b32 v50, v178, v241
	global_load_dwordx4 v[46:49], v[46:47], off
	s_waitcnt lgkmcnt(0)
	v_mad_i64_i32 v[50:51], s[6:7], v50, s62, v[150:151]
	v_mfma_f32_16x16x32_bf16 v[118:121], v[90:93], v[62:65], v[118:121]
	ds_bpermute_b32 v62, v179, v241
	global_load_dwordx4 v[50:53], v[50:51], off
	s_waitcnt lgkmcnt(0)
	v_mad_i64_i32 v[62:63], s[6:7], v62, s62, v[150:151]
	v_mfma_f32_16x16x32_bf16 v[122:125], v[90:93], v[74:77], v[122:125]
	ds_bpermute_b32 v74, v180, v241
	global_load_dwordx4 v[62:65], v[62:63], off
	s_waitcnt lgkmcnt(0)
	v_mad_i64_i32 v[74:75], s[6:7], v74, s62, v[150:151]
	v_mfma_f32_16x16x32_bf16 v[126:129], v[90:93], v[134:137], v[126:129]
	ds_bpermute_b32 v90, v181, v241
	global_load_dwordx4 v[74:77], v[74:75], off
	s_waitcnt lgkmcnt(0)
	v_mad_i64_i32 v[90:91], s[6:7], v90, s62, v[150:151]
	global_load_dwordx4 v[90:93], v[90:91], off
	s_waitcnt vmcnt(23)
	ds_write_b128 v249, v[2:5] offset:2048
	s_waitcnt vmcnt(22)
	ds_write_b128 v250, v[10:13] offset:3072
	s_waitcnt vmcnt(21)
	ds_write_b128 v251, v[18:21] offset:4096
	s_waitcnt vmcnt(20)
	ds_write_b128 v240, v[30:33] offset:5120
	s_waitcnt vmcnt(19)
	ds_write_b128 v249, v[54:57] offset:6144
	s_waitcnt vmcnt(18)
	ds_write_b128 v250, v[66:69] offset:7168
	s_waitcnt vmcnt(17)
	ds_write_b128 v251, v[78:81] offset:8192
	s_waitcnt vmcnt(16)
	ds_write_b128 v240, v[98:101] offset:9216
	s_waitcnt lgkmcnt(0)
	v_mov_b32_e32 v2, 0
	v_mov_b32_e32 v10, 0
	v_mov_b32_e32 v11, 0
	v_mov_b32_e32 v12, 0
	v_mov_b32_e32 v13, 0
	s_and_saveexec_b64 s[6:7], s[0:1]
	ds_read_b128 v[10:13], v149 offset:256
	s_or_b64 exec, exec, s[6:7]
	ds_read_b64_tr_b16 v[18:19], v139
	ds_read_b64_tr_b16 v[20:21], v152
	ds_read_b64_tr_b16 v[30:31], v153
	ds_read_b64_tr_b16 v[32:33], v154
	ds_read_b64_tr_b16 v[54:55], v155
	ds_read_b64_tr_b16 v[56:57], v156
	ds_read_b64_tr_b16 v[66:67], v157
	ds_read_b64_tr_b16 v[68:69], v158
	ds_bpermute_b32 v3, v168, v241
	ds_read_b64_tr_b16 v[78:79], v159
	ds_read_b64_tr_b16 v[80:81], v160
	ds_read_b64_tr_b16 v[98:99], v161
	ds_read_b64_tr_b16 v[100:101], v162
	ds_read_b64_tr_b16 v[190:191], v163
	s_waitcnt lgkmcnt(0)
	v_mad_i64_i32 v[4:5], s[6:7], v3, s62, v[150:151]
	ds_bpermute_b32 v3, v182, v241
	ds_read_b64_tr_b16 v[192:193], v164
	ds_read_b64_tr_b16 v[194:195], v165
	ds_read_b64_tr_b16 v[196:197], v166
	s_nop 0
	s_waitcnt lgkmcnt(0)
	s_nop 0
	v_mfma_f32_16x16x32_bf16 v[130:133], v[10:13], v[18:21], v[94:97]
	v_mfma_f32_16x16x32_bf16 v[134:137], v[10:13], v[30:33], v[102:105]
	v_mfma_f32_16x16x32_bf16 v[106:109], v[10:13], v[54:57], v[106:109]
	v_mfma_f32_16x16x32_bf16 v[110:113], v[10:13], v[66:69], v[110:113]
	v_mfma_f32_16x16x32_bf16 v[114:117], v[10:13], v[78:81], v[114:117]
	v_mfma_f32_16x16x32_bf16 v[118:121], v[10:13], v[98:101], v[118:121]
	v_mfma_f32_16x16x32_bf16 v[102:105], v[10:13], v[190:193], v[122:125]
	v_mfma_f32_16x16x32_bf16 v[98:101], v[10:13], v[194:197], v[126:129]
	global_load_dwordx4 v[10:13], v[4:5], off
	s_waitcnt lgkmcnt(0)
	v_mad_i64_i32 v[4:5], s[6:7], v3, s62, v[150:151]
	ds_bpermute_b32 v3, v183, v241
	global_load_dwordx4 v[18:21], v[4:5], off
	s_waitcnt lgkmcnt(0)
	v_mad_i64_i32 v[4:5], s[6:7], v3, s62, v[150:151]
	ds_bpermute_b32 v3, v184, v241
	global_load_dwordx4 v[30:33], v[4:5], off
	s_waitcnt lgkmcnt(0)
	v_mad_i64_i32 v[4:5], s[6:7], v3, s62, v[150:151]
	ds_bpermute_b32 v3, v185, v241
	global_load_dwordx4 v[54:57], v[4:5], off
	s_waitcnt lgkmcnt(0)
	v_mad_i64_i32 v[4:5], s[6:7], v3, s62, v[150:151]
	ds_bpermute_b32 v3, v186, v241
	global_load_dwordx4 v[66:69], v[4:5], off
	s_waitcnt lgkmcnt(0)
	v_mad_i64_i32 v[4:5], s[6:7], v3, s62, v[150:151]
	ds_bpermute_b32 v3, v187, v241
	global_load_dwordx4 v[78:81], v[4:5], off
	s_waitcnt lgkmcnt(0)
	v_mad_i64_i32 v[4:5], s[6:7], v3, s62, v[150:151]
	ds_bpermute_b32 v3, v188, v241
	global_load_dwordx4 v[94:97], v[4:5], off
	s_waitcnt lgkmcnt(0)
	v_mad_i64_i32 v[4:5], s[6:7], v3, s62, v[150:151]
	global_load_dwordx4 v[122:125], v[4:5], off
	s_waitcnt vmcnt(22)
	ds_write_b128 v249, v[6:9] offset:2048
	s_waitcnt vmcnt(21)
	ds_write_b128 v250, v[14:17] offset:3072
	s_waitcnt vmcnt(20)
	ds_write_b128 v251, v[26:29] offset:4096
	s_waitcnt vmcnt(19)
	ds_write_b128 v240, v[34:37] offset:5120
	s_waitcnt vmcnt(18)
	ds_write_b128 v249, v[58:61] offset:6144
	s_waitcnt vmcnt(17)
	ds_write_b128 v250, v[70:73] offset:7168
	ds_write_b128 v251, v[82:85] offset:8192
	s_waitcnt vmcnt(16)
	ds_write_b128 v240, v[86:89] offset:9216
	s_waitcnt lgkmcnt(0)
; #define LAS __attribute__((address_space(3)))
; #define ATTN_VLOAD(dst, ks) do { const int sreg_ = ((ks) < 2) ? s0 : ((ks) < 4) ? s1 : ((ks) < 6) ? s2 : s3; _Pragma("unroll") for (int i = 0; i < 8; ++i) { \
;             const int idx_ = shi(sreg_, 32 * ((ks) & 1) + fq + 4 * i); dst[i] = *(const u32x4*)(vbase + (size_t)idx_ * DSA_NP); } } while (0)
; __device__ __forceinline__ void dsa_attn(const bf16_t* DP, const int* SEL, bf16_t* O, LAS unsigned char* lds, int widk) {
;     ...
; #pragma unroll
;         for (int ks = 0; ks < 8; ++ks) {
;             if (ks < 6) ATTN_VLOAD(vnn, ks + 2);
; #pragma unroll
;             for (int i = 0; i < 8; ++i) { const unsigned row = (unsigned)(fq + 4 * i), ch = (unsigned)fr;
;                 *(LAS u32x4*)(vt + 256u * row + 16u * (ch ^ (((row & 3u) << 2) | ((row >> 2) & 3u)))) = vcur[i]; }
;             bf16x8 pa = (bf16x8){0, 0, 0, 0, 0, 0, 0, 0};
;             asm volatile("s_waitcnt lgkmcnt(0)" ::: "memory");
;             if (fr < 4) pa = *(const LAS bf16x8*)(pl + (fr * 256 + 32 * ks + 8 * fq) * 2);
;             u32x2 t0[8], t1[8];
; #pragma unroll
;             for (int cb = 0; cb < 8; ++cb) {
;                 asm volatile("ds_read_b64_tr_b16 %0, %1" : "=v"(t0[cb]) : "v"(tra[cb][0]) : "memory");
;                 asm volatile("ds_read_b64_tr_b16 %0, %1" : "=v"(t1[cb]) : "v"(tra[cb][1]) : "memory");
;             }
;             asm volatile("s_waitcnt lgkmcnt(0)" : "+v"(t0[0]), "+v"(t0[1]), "+v"(t0[2]), "+v"(t0[3]), "+v"(t0[4]), "+v"(t0[5]), "+v"(t0[6]), "+v"(t0[7]),
;                                                   "+v"(t1[0]), "+v"(t1[1]), "+v"(t1[2]), "+v"(t1[3]), "+v"(t1[4]), "+v"(t1[5]), "+v"(t1[6]), "+v"(t1[7]), "+v"(pa) :: "memory");
; #pragma unroll
;             for (int cb = 0; cb < 8; ++cb) { const u32x4 bw = {t0[cb].x, t0[cb].y, t1[cb].x, t1[cb].y};
;                 oc[cb] = __builtin_amdgcn_mfma_f32_16x16x32_bf16(pa, __builtin_bit_cast(bf16x8, bw), oc[cb], 0, 0, 0); }
; #pragma unroll
;             for (int i = 0; i < 8; ++i) { vcur[i] = vnxt[i]; vnxt[i] = vnn[i]; }
;         }
;     ...
;         if (fq == 0) {
	v_mov_b32_e32 v3, 0
	v_mov_b32_e32 v4, 0
	v_mov_b32_e32 v5, 0
	s_and_saveexec_b64 s[6:7], s[0:1]
	ds_read_b128 v[2:5], v149 offset:320
	s_or_b64 exec, exec, s[6:7]
	ds_read_b64_tr_b16 v[6:7], v139
	ds_read_b64_tr_b16 v[8:9], v152
	ds_read_b64_tr_b16 v[14:15], v153
	ds_read_b64_tr_b16 v[16:17], v154
	ds_read_b64_tr_b16 v[26:27], v155
	ds_read_b64_tr_b16 v[28:29], v156
	ds_read_b64_tr_b16 v[34:35], v157
	ds_read_b64_tr_b16 v[36:37], v158
	ds_read_b64_tr_b16 v[58:59], v159
	ds_read_b64_tr_b16 v[60:61], v160
	ds_read_b64_tr_b16 v[70:71], v161
	ds_read_b64_tr_b16 v[72:73], v162
	ds_read_b64_tr_b16 v[82:83], v163
	ds_read_b64_tr_b16 v[84:85], v164
	ds_read_b64_tr_b16 v[86:87], v165
	ds_read_b64_tr_b16 v[88:89], v166
	s_waitcnt lgkmcnt(0)
	s_waitcnt lgkmcnt(0)
	s_waitcnt vmcnt(15)
	ds_write_b128 v249, v[22:25] offset:2048
	s_waitcnt vmcnt(14)
	ds_write_b128 v250, v[38:41] offset:3072
	s_waitcnt vmcnt(13)
	ds_write_b128 v251, v[42:45] offset:4096
	v_mfma_f32_16x16x32_bf16 v[6:9], v[2:5], v[6:9], v[130:133]
	s_waitcnt vmcnt(12)
	ds_write_b128 v240, v[46:49] offset:5120
	s_waitcnt vmcnt(11)
	ds_write_b128 v249, v[50:53] offset:6144
	s_waitcnt vmcnt(10)
	ds_write_b128 v250, v[62:65] offset:7168
	s_waitcnt vmcnt(9)
	ds_write_b128 v251, v[74:77] offset:8192
	s_waitcnt vmcnt(8)
	ds_write_b128 v240, v[90:93] offset:9216
	s_waitcnt lgkmcnt(0)
	v_mfma_f32_16x16x32_bf16 v[14:17], v[2:5], v[14:17], v[134:137]
	v_mov_b32_e32 v50, 0
	v_mov_b32_e32 v51, 0
	v_mov_b32_e32 v52, 0
	v_mfma_f32_16x16x32_bf16 v[26:29], v[2:5], v[26:29], v[106:109]
	v_mov_b32_e32 v53, 0
	v_mfma_f32_16x16x32_bf16 v[34:37], v[2:5], v[34:37], v[110:113]
	v_mfma_f32_16x16x32_bf16 v[58:61], v[2:5], v[58:61], v[114:117]
	v_mfma_f32_16x16x32_bf16 v[70:73], v[2:5], v[70:73], v[118:121]
	v_mfma_f32_16x16x32_bf16 v[22:25], v[2:5], v[82:85], v[102:105]
	v_mfma_f32_16x16x32_bf16 v[38:41], v[2:5], v[86:89], v[98:101]
	v_mov_b32_e32 v2, 0
	s_and_saveexec_b64 s[6:7], s[0:1]
	ds_read_b128 v[50:53], v149 offset:384
	s_or_b64 exec, exec, s[6:7]
	ds_read_b64_tr_b16 v[42:43], v139
	ds_read_b64_tr_b16 v[44:45], v152
	ds_read_b64_tr_b16 v[46:47], v153
	ds_read_b64_tr_b16 v[48:49], v154
	ds_read_b64_tr_b16 v[62:63], v155
	ds_read_b64_tr_b16 v[64:65], v156
	ds_read_b64_tr_b16 v[74:75], v157
	ds_read_b64_tr_b16 v[76:77], v158
	ds_read_b64_tr_b16 v[82:83], v159
	ds_read_b64_tr_b16 v[84:85], v160
	ds_read_b64_tr_b16 v[86:87], v161
	ds_read_b64_tr_b16 v[88:89], v162
	ds_read_b64_tr_b16 v[90:91], v163
	ds_read_b64_tr_b16 v[92:93], v164
	ds_read_b64_tr_b16 v[98:99], v165
	ds_read_b64_tr_b16 v[100:101], v166
	v_mov_b32_e32 v3, 0
	s_waitcnt lgkmcnt(0)
	s_waitcnt lgkmcnt(0)
	s_waitcnt vmcnt(7)
	ds_write_b128 v249, v[10:13] offset:2048
	s_waitcnt vmcnt(6)
	ds_write_b128 v250, v[18:21] offset:3072
	s_waitcnt vmcnt(5)
	ds_write_b128 v251, v[30:33] offset:4096
	v_mfma_f32_16x16x32_bf16 v[6:9], v[50:53], v[42:45], v[6:9]
	s_waitcnt vmcnt(4)
	ds_write_b128 v240, v[54:57] offset:5120
	s_waitcnt vmcnt(3)
	ds_write_b128 v249, v[66:69] offset:6144
	s_waitcnt vmcnt(2)
	ds_write_b128 v250, v[78:81] offset:7168
	s_waitcnt vmcnt(1)
	ds_write_b128 v251, v[94:97] offset:8192
	s_waitcnt vmcnt(0)
	ds_write_b128 v240, v[122:125] offset:9216
	s_waitcnt lgkmcnt(0)
	v_mfma_f32_16x16x32_bf16 v[14:17], v[50:53], v[46:49], v[14:17]
	v_mov_b32_e32 v4, 0
	v_mov_b32_e32 v5, 0
	v_mfma_f32_16x16x32_bf16 v[26:29], v[50:53], v[62:65], v[26:29]
	v_mfma_f32_16x16x32_bf16 v[34:37], v[50:53], v[74:77], v[34:37]
	v_mfma_f32_16x16x32_bf16 v[42:45], v[50:53], v[82:85], v[58:61]
	v_mfma_f32_16x16x32_bf16 v[46:49], v[50:53], v[86:89], v[70:73]
	v_mfma_f32_16x16x32_bf16 v[18:21], v[50:53], v[90:93], v[22:25]
	v_mfma_f32_16x16x32_bf16 v[10:13], v[50:53], v[98:101], v[38:41]
	s_and_saveexec_b64 s[6:7], s[0:1]
	ds_read_b128 v[2:5], v149 offset:448
	s_or_b64 exec, exec, s[6:7]
	ds_read_b64_tr_b16 v[22:23], v139
	ds_read_b64_tr_b16 v[24:25], v152
	ds_read_b64_tr_b16 v[30:31], v153
	ds_read_b64_tr_b16 v[32:33], v154
	ds_read_b64_tr_b16 v[54:55], v155
	ds_read_b64_tr_b16 v[56:57], v156
	ds_read_b64_tr_b16 v[58:59], v157
	ds_read_b64_tr_b16 v[60:61], v158
	ds_read_b64_tr_b16 v[62:63], v159
	ds_read_b64_tr_b16 v[64:65], v160
	ds_read_b64_tr_b16 v[66:67], v161
	ds_read_b64_tr_b16 v[68:69], v162
	ds_read_b64_tr_b16 v[70:71], v163
	ds_read_b64_tr_b16 v[72:73], v164
	ds_read_b64_tr_b16 v[74:75], v165
	ds_read_b64_tr_b16 v[76:77], v166
	s_waitcnt lgkmcnt(0)
	s_waitcnt lgkmcnt(0)
	s_nop 0
	v_mfma_f32_16x16x32_bf16 v[50:53], v[2:5], v[22:25], v[6:9]
	v_mfma_f32_16x16x32_bf16 v[38:41], v[2:5], v[30:33], v[14:17]
	v_mfma_f32_16x16x32_bf16 v[30:33], v[2:5], v[54:57], v[26:29]
	v_mfma_f32_16x16x32_bf16 v[26:29], v[2:5], v[58:61], v[34:37]
	v_mfma_f32_16x16x32_bf16 v[22:25], v[2:5], v[62:65], v[42:45]
	v_mfma_f32_16x16x32_bf16 v[14:17], v[2:5], v[66:69], v[46:49]
	v_mfma_f32_16x16x32_bf16 v[6:9], v[2:5], v[70:73], v[18:21]
	v_mfma_f32_16x16x32_bf16 v[2:5], v[2:5], v[74:77], v[10:13]
	s_and_saveexec_b64 s[6:7], s[2:3]
	s_cbranch_execz .LBB0_662
; __device__ __forceinline__ unsigned f2bf(float f) { unsigned u = __float_as_uint(f); return (u + 0x7fffu + ((u >> 16) & 1u)) >> 16; }
; __device__ __forceinline__ void dsa_attn(const bf16_t* DP, const int* SEL, bf16_t* O, LAS unsigned char* lds, int widk) {
;     ...
;         if (fq == 0) {
;             bf16_t* op = O + tok * D + (g * 4) * 128 + fr;
; #pragma unroll
;             for (int cb = 0; cb < 8; ++cb)
; #pragma unroll
;                 for (int r = 0; r < 4; ++r) op[r * 128 + 16 * cb] = (bf16_t)f2bf(oc[cb][r]);
;         }
	v_lshrrev_b32_e32 v18, 2, v143
	v_mul_u32_u24_e32 v19, 0x1fe, v18
	v_sub_u32_e32 v19, v171, v19
	v_bfe_u32 v12, v50, 16, 1
	v_add3_u32 v12, v50, v12, s77
	ds_write_b16_d16_hi v19, v12
	v_bfe_u32 v13, v51, 16, 1
	v_add3_u32 v13, v51, v13, s77
	ds_write_b16_d16_hi v19, v13 offset:256
	v_bfe_u32 v12, v52, 16, 1
	v_add3_u32 v12, v52, v12, s77
	ds_write_b16_d16_hi v19, v12 offset:512
	v_bfe_u32 v13, v53, 16, 1
	v_add3_u32 v13, v53, v13, s77
	ds_write_b16_d16_hi v19, v13 offset:768
	v_bfe_u32 v12, v38, 16, 1
	v_add3_u32 v12, v38, v12, s77
	ds_write_b16_d16_hi v19, v12 offset:32
	v_bfe_u32 v13, v39, 16, 1
	v_add3_u32 v13, v39, v13, s77
	ds_write_b16_d16_hi v19, v13 offset:288
	v_bfe_u32 v12, v40, 16, 1
	v_add3_u32 v12, v40, v12, s77
	ds_write_b16_d16_hi v19, v12 offset:544
	v_bfe_u32 v13, v41, 16, 1
	v_add3_u32 v13, v41, v13, s77
	ds_write_b16_d16_hi v19, v13 offset:800
	v_bfe_u32 v12, v30, 16, 1
	v_add3_u32 v12, v30, v12, s77
	ds_write_b16_d16_hi v19, v12 offset:64
	v_bfe_u32 v13, v31, 16, 1
	v_add3_u32 v13, v31, v13, s77
	ds_write_b16_d16_hi v19, v13 offset:320
	v_bfe_u32 v12, v32, 16, 1
	v_add3_u32 v12, v32, v12, s77
	ds_write_b16_d16_hi v19, v12 offset:576
	v_bfe_u32 v13, v33, 16, 1
	v_add3_u32 v13, v33, v13, s77
	ds_write_b16_d16_hi v19, v13 offset:832
	v_bfe_u32 v12, v26, 16, 1
	v_add3_u32 v12, v26, v12, s77
	ds_write_b16_d16_hi v19, v12 offset:96
	v_bfe_u32 v13, v27, 16, 1
	v_add3_u32 v13, v27, v13, s77
	ds_write_b16_d16_hi v19, v13 offset:352
	v_bfe_u32 v12, v28, 16, 1
	v_add3_u32 v12, v28, v12, s77
	ds_write_b16_d16_hi v19, v12 offset:608
	v_bfe_u32 v13, v29, 16, 1
	v_add3_u32 v13, v29, v13, s77
	ds_write_b16_d16_hi v19, v13 offset:864
	v_bfe_u32 v12, v22, 16, 1
	v_add3_u32 v12, v22, v12, s77
	ds_write_b16_d16_hi v19, v12 offset:128
	v_bfe_u32 v13, v23, 16, 1
	v_add3_u32 v13, v23, v13, s77
	ds_write_b16_d16_hi v19, v13 offset:384
	v_bfe_u32 v12, v24, 16, 1
	v_add3_u32 v12, v24, v12, s77
	ds_write_b16_d16_hi v19, v12 offset:640
	v_bfe_u32 v13, v25, 16, 1
	v_add3_u32 v13, v25, v13, s77
	ds_write_b16_d16_hi v19, v13 offset:896
	v_bfe_u32 v12, v14, 16, 1
	v_add3_u32 v12, v14, v12, s77
	ds_write_b16_d16_hi v19, v12 offset:160
	v_bfe_u32 v13, v15, 16, 1
	v_add3_u32 v13, v15, v13, s77
	ds_write_b16_d16_hi v19, v13 offset:416
	v_bfe_u32 v12, v16, 16, 1
	v_add3_u32 v12, v16, v12, s77
	ds_write_b16_d16_hi v19, v12 offset:672
	v_bfe_u32 v13, v17, 16, 1
	v_add3_u32 v13, v17, v13, s77
	ds_write_b16_d16_hi v19, v13 offset:928
	v_bfe_u32 v12, v6, 16, 1
	v_add3_u32 v12, v6, v12, s77
	ds_write_b16_d16_hi v19, v12 offset:192
	v_bfe_u32 v13, v7, 16, 1
	v_add3_u32 v13, v7, v13, s77
	ds_write_b16_d16_hi v19, v13 offset:448
	v_bfe_u32 v12, v8, 16, 1
	v_add3_u32 v12, v8, v12, s77
	ds_write_b16_d16_hi v19, v12 offset:704
	v_bfe_u32 v13, v9, 16, 1
	v_add3_u32 v13, v9, v13, s77
	ds_write_b16_d16_hi v19, v13 offset:960
	v_bfe_u32 v12, v2, 16, 1
	v_add3_u32 v12, v2, v12, s77
	ds_write_b16_d16_hi v19, v12 offset:224
	v_bfe_u32 v13, v3, 16, 1
	v_add3_u32 v13, v3, v13, s77
	ds_write_b16_d16_hi v19, v13 offset:480
	v_bfe_u32 v12, v4, 16, 1
	v_add3_u32 v12, v4, v12, s77
	ds_write_b16_d16_hi v19, v12 offset:736
	v_bfe_u32 v13, v5, 16, 1
	v_add3_u32 v13, v5, v13, s77
	ds_write_b16_d16_hi v19, v13 offset:992
	s_or_b64 exec, exec, s[6:7]
	s_lshl_b64 s[4:5], s[4:5], 12
	v_lshl_add_u64 v[10:11], v[146:147], 0, s[4:5]
	v_lshrrev_b32_e32 v18, 2, v143
	v_mul_u32_u24_e32 v20, 14, v18
	v_lshl_add_u32 v20, v142, 4, v20
	v_mov_b32_e32 v21, 0
	v_lshl_add_u64 v[10:11], v[10:11], 0, v[20:21]
	v_mul_u32_u24_e32 v12, 0x1f0, v18
	v_sub_u32_e32 v12, v171, v12
	v_lshl_add_u32 v12, v142, 4, v12
	s_waitcnt lgkmcnt(0)
	ds_read_b128 v[34:37], v12
	s_waitcnt lgkmcnt(0)
	global_store_dwordx4 v[10:11], v[34:37], off
	s_branch .LBB0_662
